# planAW_v3 + sync-path trimming: redundant workgroup barrier removed before early mixer pass, poll sleeps shortened
# baseline (speedup 1.0000x reference)
; #define GRID_BAR() xcd_barrier(xbar)
; __global__ void __launch_bounds__(512, 2) fwd_megakernel(Params p) {
;     ...
;             GRID_BAR();
.Lpa_gw_loop:
	global_load_dword v3, v2, s[98:99] sc1
	s_waitcnt vmcnt(0)
	v_readfirstlane_b32 vcc_lo, v3
	s_cmpk_ge_u32 vcc_lo, 32
	s_cbranch_scc1 .Lpa_gw_acq
	s_sleep 1
	s_add_u32 vcc_hi, vcc_hi, 1
	s_cmp_lt_u32 vcc_hi, 0x100000
	s_cbranch_scc1 .Lpa_gw_loop

; __global__ void __launch_bounds__(512, 2) fwd_megakernel(Params p) {
;     ...
;               { pg8::Gemm g{act, wd, MT, DM, DFF, DFF / 256}; pg8::SplitOrder S{(int)blockIdx.x, (DFF / 4) * 2};
;                 pg8::EpiSlab E{(float*)(p.ws + WS_SLAB), 0.5f, (DFF / 4) * 2};
;                 pg8::gemm_phase<pg8::EpiSlab, pg8::SplitOrder, true, true>(lds, g, S, E); } }
.Lpa_sw_loop:
	global_load_dword v1, v0, s[98:99] sc1
	s_waitcnt vmcnt(0)
	v_readfirstlane_b32 s100, v1
	s_cmpk_ge_u32 s100, 88
	s_cbranch_scc1 .Lpa_sw_acq
	s_sleep 1
	s_add_u32 s101, s101, 1
	s_cmp_lt_u32 s101, 0x100000
	s_cbranch_scc1 .Lpa_sw_loop

; #define GRID_BAR() xcd_barrier(xbar)
; __global__ void __launch_bounds__(512, 2) fwd_megakernel(Params p) {
;     ...
;             GRID_BAR();
; #pragma unroll 1
;             for (int rep = 0; rep < REP_MIX; ++rep)
;             mixer_mid(p, lds, G, layer);
.Lpw_gw_done:
	s_or_b64 exec, exec, s[100:101]
	v_readlane_b32 s100, v244, 9
	s_sub_u32 s100, s100, 32
	v_writelane_b32 v244, s100, 9
	s_mov_b32 s100, 4
	s_nop 0
	v_writelane_b32 v244, s100, 10
	s_mov_b32 s101, 1
	s_branch .Lpw_mixer_entry
